# attention phase: one static s_setprio 1 for waves 0-3 (the other half than tried before), reset before the following grid barrier
# baseline (speedup 1.0000x reference)
.LBB0_282:
	v_cvt_f32_u32_e32 v0, s94
	s_mov_b32 s4, 0x3fb8aa3b
	s_waitcnt vmcnt(24)
	v_fma_f32 v114, v114, v118, 0
	s_mov_b32 s5, 0xc2ce8ed0
	v_mul_f32_e32 v0, 0xbe99999a, v0
	v_mul_f32_e32 v130, 0x3fb8aa3b, v0
	v_fma_f32 v131, v0, s4, -v130
	v_rndne_f32_e32 v132, v130
	v_fmac_f32_e32 v131, 0x32a5705f, v0
	v_sub_f32_e32 v130, v130, v132
	v_add_f32_e32 v130, v130, v131
	v_cvt_i32_f32_e32 v132, v132
	v_exp_f32_e32 v130, v130
	v_cmp_ngt_f32_e32 vcc, s5, v0
	s_mov_b32 s7, 0x42b17218
	v_fmac_f32_e32 v114, v115, v119
	v_ldexp_f32 v118, v130, v132
	v_cndmask_b32_e32 v118, 0, v118, vcc
	v_cmp_nlt_f32_e32 vcc, s7, v0
	v_fmac_f32_e32 v114, v116, v120
	v_fmac_f32_e32 v114, v117, v121
	v_cndmask_b32_e32 v0, v234, v118, vcc
	s_waitcnt vmcnt(16)
	v_fma_f32 v118, v122, v126, 0
	v_fmac_f32_e32 v118, v123, v127
	v_fmac_f32_e32 v114, v98, v102
	v_fmac_f32_e32 v118, v124, v128
	v_fmac_f32_e32 v114, v99, v103
	v_fmac_f32_e32 v118, v125, v129
	v_fmac_f32_e32 v114, v100, v104
	v_fmac_f32_e32 v118, v106, v110
	v_fmac_f32_e32 v114, v101, v105
	v_fmac_f32_e32 v118, v107, v111
	v_fmac_f32_e32 v114, v82, v86
	v_fmac_f32_e32 v118, v108, v112
	v_fmac_f32_e32 v114, v83, v87
	v_fmac_f32_e32 v118, v109, v113
	v_fmac_f32_e32 v114, v84, v88
	v_fmac_f32_e32 v118, v90, v94
	v_fmac_f32_e32 v114, v85, v89
	v_fmac_f32_e32 v118, v91, v95
	v_fmac_f32_e32 v114, v50, v58
	v_fmac_f32_e32 v118, v92, v96
	v_fmac_f32_e32 v114, v51, v59
	v_fmac_f32_e32 v118, v93, v97
	v_fmac_f32_e32 v114, v52, v60
	v_fmac_f32_e32 v118, v62, v74
	v_fmac_f32_e32 v114, v53, v61
	v_fmac_f32_e32 v118, v63, v75
	s_waitcnt vmcnt(8)
	v_fmac_f32_e32 v114, v54, v66
	v_fmac_f32_e32 v118, v64, v76
	v_fmac_f32_e32 v114, v55, v67
	v_fmac_f32_e32 v118, v65, v77
	v_fmac_f32_e32 v114, v56, v68
	s_waitcnt vmcnt(0)
	v_fmac_f32_e32 v118, v70, v78
	v_fmac_f32_e32 v114, v57, v69
	v_fmac_f32_e32 v118, v71, v79
	v_fmac_f32_e32 v114, v34, v38
	v_fmac_f32_e32 v118, v72, v80
	v_fmac_f32_e32 v114, v35, v39
	v_fmac_f32_e32 v118, v73, v81
	v_fmac_f32_e32 v114, v36, v40
	v_fmac_f32_e32 v118, v42, v46
	v_fmac_f32_e32 v114, v37, v41
	v_fmac_f32_e32 v118, v43, v47
	v_fmac_f32_e32 v114, v18, v22
	v_fmac_f32_e32 v118, v44, v48
	v_fmac_f32_e32 v114, v19, v23
	v_fmac_f32_e32 v118, v45, v49
	v_fmac_f32_e32 v114, v20, v24
	v_fmac_f32_e32 v118, v26, v30
	v_fmac_f32_e32 v114, v21, v25
	v_fmac_f32_e32 v118, v27, v31
	v_fmac_f32_e32 v114, v10, v14
	v_fmac_f32_e32 v118, v28, v32
	v_fmac_f32_e32 v114, v11, v15
	v_fmac_f32_e32 v118, v29, v33
	v_fmac_f32_e32 v114, v12, v16
	v_fmac_f32_e32 v118, v2, v6
	v_fmac_f32_e32 v114, v13, v17
	v_fmac_f32_e32 v118, v3, v7
	v_mul_f32_e32 v2, 0x3fb8aa3b, v114
	v_fmac_f32_e32 v118, v4, v8
	v_fma_f32 v3, v114, s4, -v2
	v_rndne_f32_e32 v4, v2
	v_fmac_f32_e32 v3, 0x32a5705f, v114
	v_sub_f32_e32 v2, v2, v4
	v_add_f32_e32 v2, v2, v3
	v_exp_f32_e32 v2, v2
	v_cvt_i32_f32_e32 v3, v4
	v_fmac_f32_e32 v118, v5, v9
	v_cmp_ngt_f32_e32 vcc, s5, v114
	s_add_u32 s2, s2, s8
	v_ldexp_f32 v2, v2, v3
	v_mul_f32_e32 v3, 0x3fb8aa3b, v118
	v_fma_f32 v4, v118, s4, -v3
	v_rndne_f32_e32 v5, v3
	v_fmac_f32_e32 v4, 0x32a5705f, v118
	v_sub_f32_e32 v3, v3, v5
	v_add_f32_e32 v3, v3, v4
	v_exp_f32_e32 v3, v3
	v_cvt_i32_f32_e32 v4, v5
	v_cndmask_b32_e32 v2, 0, v2, vcc
	v_cmp_nlt_f32_e32 vcc, s7, v114
	s_addc_u32 s3, s3, s9
	v_ldexp_f32 v3, v3, v4
	v_cndmask_b32_e32 v2, v234, v2, vcc
	v_cmp_ngt_f32_e32 vcc, s5, v118
	s_add_u32 s58, s2, 0x1000
	s_addc_u32 s59, s3, 0
	v_cndmask_b32_e32 v3, 0, v3, vcc
	v_cmp_nlt_f32_e32 vcc, s7, v118
	v_readlane_b32 s2, v244, 11
	v_fmamk_f32 v0, v0, 0xbf19999a, v231
	v_cndmask_b32_e32 v3, v234, v3, vcc
	v_sub_f32_e32 v2, v2, v3
	s_add_u32 s7, s58, s2
	v_sub_f32_e32 v177, 1.0, v0
	v_add_f32_e32 v183, v0, v2
	s_addc_u32 s33, s59, 0
	v_readlane_b32 s100, v245, 26
	s_nop 3
	s_sub_i32 s100, s100, 0x18000
	s_cmp_lt_u32 s100, 16
	s_cbranch_scc0 .Latt_prio_done
	s_setprio 1
.Latt_prio_done:
	s_branch .LBB0_286
.LBB0_283:
	s_waitcnt vmcnt(63) expcnt(7) lgkmcnt(15)
	s_barrier
